# static s_setprio 3 (was 1) for waves 4-7 across the attention KV loop
# baseline (speedup 1.0000x reference)
; DEV int get_tid() { int t = threadIdx.x; asm volatile("" : "+v"(t)); return t; }
; DEV void attn_item(const Params& p, int layer, int h, int qb, float lam, bf16_t* lds) {
;     ...
;   const int tid = get_tid(), lane = tid & 63, wave = tid >> 6;
;   const int lr = lane & 15, lg = lane >> 4;
;   const int grp = wave >> 2, wq = wave & 3;
;   const int t0 = qb * 128;
;   const int lrow = tid >> 4, lc8 = (tid & 15) * 8;
;   const bf16_t* gq = DQ + (size_t)(t0 + wq * 32 + lr) * 1024 + h * 128 + grp * 64 + lg * 8;
;   const bf16x8 a00 = *(const bf16x8*)(gq);
;   const bf16x8 a01 = *(const bf16x8*)(gq + 32);
;   const bf16x8 a10 = *(const bf16x8*)(gq + (size_t)16 * 1024);
;   const bf16x8 a11 = *(const bf16x8*)(gq + (size_t)16 * 1024 + 32);
;   f32x4 o[2][8];
; #pragma unroll
;   for (int i = 0; i < 2; i++)
; #pragma unroll
;     for (int j = 0; j < 8; j++) o[i][j] = (f32x4){0.f, 0.f, 0.f, 0.f};
;   float mrun0 = -1e30f, mrun1 = -1e30f, lrun0 = 0.f, lrun1 = 0.f;
;   u32x4 rk0, rk1, rk2, rk3, rv0, rv1, rv2, rv3;
;   const unsigned ko = (unsigned)(lrow * 1024 + h * 128 + lc8);
;   const unsigned vo = (unsigned)((h * 128 + lrow) * LT + lc8);
;     ...
;   ALOAD(0)
;   const int qrow0 = t0 + wq * 32 + lr;
;   __syncthreads();
;   ASTORE(KV + lrow * PS + lc8)
;   {
;     const int kb1 = qb > 0 ? 1 : 0;
;     ALOAD(kb1)
.LBB0_706:
	v_mov_b32_e32 v224, v181
	s_ashr_i32 s0, s2, 3
	s_sub_i32 s76, 64, s0
	v_lshrrev_b32_e32 v2, 1, v224
	v_and_b32_e32 v226, 0x60, v2
	v_and_b32_e32 v222, 15, v224
	v_lshlrev_b32_e32 v0, 3, v224
	v_lshl_or_b32 v223, s76, 7, v226
	s_lshl_b32 s1, s2, 7
	v_ashrrev_i32_e32 v84, 4, v224
	v_or_b32_e32 v184, v223, v222
	v_mov_b32_e32 v185, v1
	v_readlane_b32 s6, v254, 55
	s_and_b32 s75, s1, 0x380
	v_and_b32_e32 v85, 0x78, v0
	v_lshlrev_b32_e32 v0, 10, v84
	v_ashrrev_i32_e32 v225, 8, v224
	v_lshlrev_b64 v[2:3], 11, v[184:185]
	v_readlane_b32 s7, v254, 56
	v_or3_b32 v186, v0, s75, v85
	v_add_u32_e32 v0, s75, v84
	s_movk_i32 s1, 0x2080
	v_lshl_add_u64 v[2:3], s[6:7], 0, v[2:3]
	s_lshl_b32 s82, s75, 1
	v_lshlrev_b32_e32 v4, 6, v225
	v_mul_lo_u32 v0, v0, s1
	v_lshl_add_u64 v[2:3], v[2:3], 0, s[82:83]
	v_ashrrev_i32_e32 v5, 31, v4
	v_or_b32_e32 v188, v0, v85
	v_mov_b32_e32 v187, v1
	v_add_u32_e32 v0, 0x8000, v186
	v_lshl_add_u64 v[2:3], v[4:5], 1, v[2:3]
	v_lshl_add_u64 v[4:5], v[186:187], 1, s[78:79]
	v_lshl_add_u64 v[6:7], v[0:1], 1, s[78:79]
	v_add_u32_e32 v0, 0x10000, v186
	global_load_dwordx4 v[52:55], v[4:5], off
	global_load_dwordx4 v[56:59], v[6:7], off
	v_lshl_add_u64 v[4:5], v[0:1], 1, s[78:79]
	v_add_u32_e32 v0, 0x18000, v186
	v_lshl_add_u64 v[6:7], v[0:1], 1, s[78:79]
	v_mov_b32_e32 v189, v1
	v_add_u32_e32 v0, 0x41000, v188
	global_load_dwordx4 v[60:63], v[4:5], off
	global_load_dwordx4 v[64:67], v[6:7], off
	v_lshl_add_u64 v[4:5], v[188:189], 1, s[70:71]
	v_lshl_add_u64 v[6:7], v[0:1], 1, s[70:71]
	v_add_u32_e32 v0, 0x82000, v188
	v_and_b32_e32 v182, 48, v224
	v_mov_b32_e32 v183, v1
	global_load_dwordx4 v[68:71], v[4:5], off
	global_load_dwordx4 v[72:75], v[6:7], off
	v_lshl_add_u64 v[4:5], v[0:1], 1, s[70:71]
	v_add_u32_e32 v0, 0xc3000, v188
	global_load_dwordx4 v[76:79], v[4:5], off
	v_lshl_add_u64 v[4:5], v[0:1], 1, s[70:71]
	v_lshl_add_u64 v[2:3], v[2:3], 0, v[182:183]
	s_mov_b32 s1, 0x8000
	s_cmp_eq_u32 s0, 64
	global_load_dwordx4 v[80:83], v[4:5], off
	s_nop 0
	global_load_dwordx4 v[4:7], v[2:3], off
	global_load_dwordx4 v[8:11], v[2:3], off offset:64
	v_add_co_u32_e32 v2, vcc, s1, v2
	s_cselect_b32 s1, 0, 0x20000
	v_add_u32_e32 v0, s1, v186
	v_addc_co_u32_e32 v3, vcc, 0, v3, vcc
	v_add_u32_e32 v20, 0x8000, v0
	v_mov_b32_e32 v21, v1
	global_load_dwordx4 v[12:15], v[2:3], off
	global_load_dwordx4 v[16:19], v[2:3], off offset:64
	v_lshl_add_u64 v[2:3], v[0:1], 1, s[78:79]
	v_lshl_add_u64 v[24:25], v[20:21], 1, s[78:79]
	s_barrier
; DEV void attn_item(const Params& p, int layer, int h, int qb, float lam, bf16_t* lds) {
;     ...
;   f32x4 o[2][8];
; #pragma unroll
;   for (int i = 0; i < 2; i++)
; #pragma unroll
;     for (int j = 0; j < 8; j++) o[i][j] = (f32x4){0.f, 0.f, 0.f, 0.f};
;   float mrun0 = -1e30f, mrun1 = -1e30f, lrun0 = 0.f, lrun1 = 0.f;
;   u32x4 rk0, rk1, rk2, rk3, rv0, rv1, rv2, rv3;
;   const unsigned ko = (unsigned)(lrow * 1024 + h * 128 + lc8);
;   const unsigned vo = (unsigned)((h * 128 + lrow) * LT + lc8);
;     ...
;   ALOAD(0)
;   const int qrow0 = t0 + wq * 32 + lr;
;   __syncthreads();
;   ASTORE(KV + lrow * PS + lc8)
;   {
;     const int kb1 = qb > 0 ? 1 : 0;
;     ALOAD(kb1)
;   }
;   __syncthreads();
;   for (int kb = 0; kb <= qb; kb++) {
;     const int cur = kb & 1;
;     const bf16_t* kp = KV + cur * TS + lr * PS + grp * 64 + lg * 8;
;     const bf16_t* vq = KV + 2 * TS + cur * TS + lr * PS + lg * 4;
	global_load_dwordx4 v[20:23], v[2:3], off
	s_nop 0
	global_load_dwordx4 v[24:27], v[24:25], off
	v_add_u32_e32 v2, 0x10000, v0
	v_add_u32_e32 v0, 0x18000, v0
	s_cselect_b32 s1, 0, 0x80
	v_mov_b32_e32 v3, v1
	v_lshl_add_u64 v[32:33], v[0:1], 1, s[78:79]
	v_add_u32_e32 v0, s1, v188
	v_lshl_add_u64 v[2:3], v[2:3], 1, s[78:79]
	v_add_u32_e32 v36, 0x41000, v0
	v_mov_b32_e32 v37, v1
	global_load_dwordx4 v[28:31], v[2:3], off
	s_nop 0
	global_load_dwordx4 v[32:35], v[32:33], off
	v_lshl_add_u64 v[2:3], v[0:1], 1, s[70:71]
	v_lshl_add_u64 v[40:41], v[36:37], 1, s[70:71]
	global_load_dwordx4 v[36:39], v[2:3], off
	s_nop 0
	global_load_dwordx4 v[40:43], v[40:41], off
	v_add_u32_e32 v2, 0x82000, v0
	v_mov_b32_e32 v3, v1
	v_add_u32_e32 v0, 0xc3000, v0
	v_lshl_add_u64 v[2:3], v[2:3], 1, s[70:71]
	v_lshl_add_u64 v[48:49], v[0:1], 1, s[70:71]
	global_load_dwordx4 v[44:47], v[2:3], off
	s_nop 0
	global_load_dwordx4 v[48:51], v[48:49], off
	s_movk_i32 s1, 0x110
	v_mul_lo_u32 v84, v84, s1
	v_lshlrev_b32_e32 v85, 1, v85
	v_add3_u32 v230, 0, v84, v85
	v_and_b32_e32 v0, 15, v181
	v_bfe_u32 v2, v181, 4, 4
	v_not_b32_e32 v3, v2
	v_and_b32_e32 v3, 1, v3
	v_lshlrev_b32_e32 v3, 1, v3
	v_add_u32_e32 v2, 4, v2
	v_bfe_u32 v2, v2, 3, 1
	v_or_b32_e32 v3, v3, v2
	v_xor_b32_e32 v3, v3, v0
	v_sub_u32_e32 v3, v3, v0
	v_lshl_add_u32 v230, v3, 4, v230
	s_waitcnt vmcnt(19)
	ds_write_b128 v230, v[52:55]
	s_waitcnt vmcnt(18)
	ds_write_b128 v230, v[56:59] offset:8704
	s_waitcnt vmcnt(17)
	ds_write_b128 v230, v[60:63] offset:17408
	s_waitcnt vmcnt(16)
	ds_write_b128 v230, v[64:67] offset:26112
	s_mov_b32 s98, 0x11000
	v_and_b32_e32 v0, 15, v181
	v_bfe_u32 v2, v181, 4, 4
	v_not_b32_e32 v54, v2
	v_and_b32_e32 v54, 1, v54
	v_lshlrev_b32_e32 v54, 1, v54
	v_add_u32_e32 v55, 4, v2
	v_bfe_u32 v55, v55, 3, 1
	v_or_b32_e32 v54, v54, v55
	v_xor_b32_e32 v3, v0, v54
	v_lshlrev_b32_e32 v3, 4, v3
	v_sub_u32_e32 v3, v230, v3
	v_add_u32_e32 v3, s98, v3
	v_lshrrev_b32_e32 v55, 2, v0
	v_lshl_add_u32 v3, v55, 6, v3
	v_bfe_u32 v55, v0, 1, 1
	v_lshl_add_u32 v3, v55, 3, v3
	v_and_b32_e32 v55, 1, v0
	v_lshlrev_b32_e32 v55, 1, v55
	v_xor_b32_e32 v55, v55, v54
	v_xor_b32_e32 v54, 1, v55
	v_lshl_add_u32 v52, v55, 4, v3
	v_lshl_add_u32 v53, v54, 4, v3
	v_mov_b32_e32 v204, v52
	v_mov_b32_e32 v205, v53
	v_bfe_u32 v2, v224, 4, 2
	v_not_b32_e32 v3, v222
	v_and_b32_e32 v3, 1, v3
	v_lshlrev_b32_e32 v3, 1, v3
	v_add_u32_e32 v55, 4, v222
	v_bfe_u32 v55, v55, 3, 1
	v_or_b32_e32 v3, v3, v55
	v_xor_b32_e32 v3, v3, v2
	v_lshlrev_b32_e32 v3, 4, v3
	v_readlane_b32 s1, v255, 8
	s_waitcnt vmcnt(15)
	ds_write_b64 v52, v[68:69]
	ds_write_b64 v53, v[70:71]
	s_waitcnt vmcnt(14)
	ds_write_b64 v52, v[72:73] offset:8704
	ds_write_b64 v53, v[74:75] offset:8704
	s_waitcnt vmcnt(13)
	ds_write_b64 v52, v[76:77] offset:17408
	ds_write_b64 v53, v[78:79] offset:17408
	v_and_b32_e32 v0, 63, v224
	v_lshlrev_b32_e32 v54, 7, v225
	v_lshlrev_b32_e32 v183, 2, v2
	s_waitcnt vmcnt(12)
	ds_write_b64 v52, v[80:81] offset:26112
	ds_write_b64 v53, v[82:83] offset:26112
	v_mul_u32_u24_e32 v52, 0x88, v222
	v_lshlrev_b32_e32 v52, 1, v52
	v_add_u32_e32 v53, 0, v52
	v_add3_u32 v232, s1, v52, v3
	v_add3_u32 v231, v53, v54, v3
	v_mov_b32_e32 v2, v1
	v_mov_b32_e32 v3, v1
	v_lshlrev_b32_e32 v185, 2, v0
	v_mov_b32_e32 v0, v1
	v_mov_b32_e32 v192, 0xf149f2ca
	v_mov_b32_e32 v190, 0
	v_mov_b64_e32 v[58:59], v[2:3]
	v_mov_b64_e32 v[62:63], v[2:3]
	v_mov_b64_e32 v[66:67], v[2:3]
	v_mov_b64_e32 v[70:71], v[2:3]
	v_mov_b64_e32 v[74:75], v[2:3]
	v_mov_b64_e32 v[78:79], v[2:3]
	v_mov_b64_e32 v[82:83], v[2:3]
	v_mov_b64_e32 v[86:87], v[2:3]
	v_mov_b64_e32 v[106:107], v[2:3]
	v_mov_b64_e32 v[90:91], v[2:3]
	v_mov_b64_e32 v[110:111], v[2:3]
	v_mov_b64_e32 v[94:95], v[2:3]
	v_mov_b64_e32 v[114:115], v[2:3]
	v_mov_b64_e32 v[98:99], v[2:3]
	v_mov_b64_e32 v[102:103], v[2:3]
	v_mov_b64_e32 v[54:55], v[2:3]
	v_mov_b32_e32 v217, 0x3e38aa3b
	v_mov_b32_e32 v180, 0x42000000
	s_mov_b32 s77, 0
	v_xor_b32_e32 v229, 64, v185
	v_xor_b32_e32 v228, 0x80, v185
	v_or_b32_e32 v233, 16, v184
	v_or_b32_e32 v227, 4, v182
	v_or_b32_e32 v189, 8, v182
	v_or_b32_e32 v187, 12, v182
	s_sub_i32 s82, 0x41, s0
	v_mov_b32_e32 v234, v183
	v_mov_b64_e32 v[56:57], v[0:1]
	v_mov_b64_e32 v[60:61], v[0:1]
	v_mov_b64_e32 v[64:65], v[0:1]
	v_mov_b64_e32 v[68:69], v[0:1]
	v_mov_b64_e32 v[72:73], v[0:1]
	v_mov_b64_e32 v[76:77], v[0:1]
	v_mov_b64_e32 v[80:81], v[0:1]
	v_mov_b64_e32 v[84:85], v[0:1]
	v_mov_b64_e32 v[104:105], v[0:1]
	v_mov_b64_e32 v[88:89], v[0:1]
	v_mov_b64_e32 v[108:109], v[0:1]
	v_mov_b64_e32 v[92:93], v[0:1]
	v_mov_b64_e32 v[112:113], v[0:1]
	v_mov_b64_e32 v[96:97], v[0:1]
	v_mov_b64_e32 v[100:101], v[0:1]
	v_mov_b64_e32 v[52:53], v[0:1]
	v_mov_b32_e32 v191, v190
	v_mov_b32_e32 v193, v192
	v_readfirstlane_b32 s99, v181
	s_lshr_b32 s99, s99, 8
	s_cmp_eq_u32 s99, 0
	s_cbranch_scc1 .Lprio_skip
	s_setprio 3
